# split-phase grid sync (arrive at start, wait at end of P0) + XCD-local seams (3us stagger) + P4/P6' epilogue rewrites
# speedup vs baseline: 1.0157x; 1.0157x over previous
.LBB0_16:
	s_or_b64 exec, exec, s[10:11]
	s_nop 0
	v_readfirstlane_b32 s4, v1
	s_nop 3
	v_writelane_b32 v255, s4, 3
	v_writelane_b32 v255, s8, 4
	v_writelane_b32 v255, s9, 5
.LBB0_20:
	s_or_b64 exec, exec, s[6:7]
	s_load_dwordx16 s[4:19], s[0:1], 0x0
	s_and_b32 s0, s20, 15
	v_writelane_b32 v254, s0, 0
	s_waitcnt lgkmcnt(0)
	s_movk_i32 s0, 0x4000
	s_lshl_b32 s44, s3, 9
	v_cmp_gt_i32_e32 vcc, s0, v64
	s_and_saveexec_b64 s[0:1], vcc
	s_cbranch_execz .LBB0_32
	v_ashrrev_i32_e32 v65, 31, v64
	s_ashr_i32 s45, s44, 31
	v_lshlrev_b64 v[0:1], 2, v[64:65]
	s_lshl_b64 s[34:35], s[44:45], 2
	s_mov_b64 s[38:39], 0
	v_mov_b32_e32 v4, 0
	s_movk_i32 s20, 0x2000
	s_movk_i32 s21, 0x800
	s_mov_b32 s22, 0x60000
	s_movk_i32 s23, 0x1000
	s_movk_i32 s24, 0x3fff
	s_mov_b64 s[40:41], s[80:81]
	s_mov_b64 s[42:43], s[6:7]
	s_mov_b64 s[46:47], s[66:67]
	v_mov_b32_e32 v5, v64
	s_branch .LBB0_26

.LBB0_58:
	s_or_b64 exec, exec, s[0:1]
	v_mbcnt_lo_u32_b32 v0, -1, 0
	v_mbcnt_hi_u32_b32 v0, -1, v0
	s_waitcnt vmcnt(0)
	s_and_b32 s0, s26, 0xffffffc0
	v_sub_u32_e32 v0, 0, v0
	v_cmp_eq_u32_e32 vcc, s0, v0
	s_barrier
	v_writelane_b32 v254, s0, 6
	s_and_saveexec_b64 s[0:1], vcc
	v_writelane_b32 v254, s64, 7
	s_nop 1
	v_writelane_b32 v254, s65, 8
	v_writelane_b32 v254, s66, 9
	v_writelane_b32 v254, s67, 10
	v_writelane_b32 v254, s42, 11
	v_writelane_b32 v254, s43, 12
	s_cbranch_execz .LBB0_110
	v_readlane_b32 s46, v255, 4
	v_readlane_b32 s47, v255, 5
	v_readlane_b32 s4, v255, 3
	s_nop 3
	s_and_b32 s4, s4, 0xffff0000
	v_mov_b32_e32 v0, 0
.Lcgw_spin:
	global_load_dword v2, v0, s[46:47] offset:32 sc1
	s_waitcnt vmcnt(0)
	v_readfirstlane_b32 s5, v2
	s_and_b32 s5, s5, 0xffff0000
	s_cmp_lg_u32 s5, s4
	s_cbranch_scc1 .Lcgw_done
	s_sleep 1
	s_branch .Lcgw_spin
.Lcgw_done:
	v_readlane_b32 s20, v254, 0
	s_nop 3
	s_lshl_b32 s21, s20, 8
	v_mov_b32_e32 v0, s21
	v_mov_b32_e32 v1, 1
	global_atomic_add v0, v1, s[36:37] offset:1024
	s_and_b32 s21, s2, 7
	s_lshl_b32 s21, s21, 2
	s_lshl_b32 s20, 1, s20
	v_mov_b32_e32 v0, s21
	v_mov_b32_e32 v1, s20
	global_atomic_or v0, v1, s[36:37] offset:32
	s_waitcnt vmcnt(0)
	s_add_i32 s4, 0, 0x20400
	v_mov_b32_e32 v0, s4
	s_waitcnt vmcnt(0) expcnt(0) lgkmcnt(0)
	ds_read_b32 v2, v0
	s_add_i32 s4, 0, 0x20404
	v_mov_b32_e32 v0, s4
	ds_read_b32 v0, v0
	s_waitcnt lgkmcnt(1)
	v_cmp_ne_u32_e32 vcc, 0, v2
	s_cbranch_vccnz .LBB0_74
	s_add_u32 s4, s66, 0x40200
	s_addc_u32 s5, s67, 0
	s_add_u32 s6, s66, 0x40400
	s_addc_u32 s7, s67, 0
	s_add_u32 s10, s66, 0x40500
	s_addc_u32 s11, s67, 0
	s_add_u32 s18, s66, 0x40600
	s_addc_u32 s19, s67, 0
	s_add_u32 s34, s66, 0x40700
	s_addc_u32 s35, s67, 0
	s_add_u32 s46, s66, 0x40800
	s_addc_u32 s47, s67, 0
	s_add_u32 s48, s66, 0x40900
	s_addc_u32 s49, s67, 0
	s_add_u32 s50, s66, 0x40a00
	s_addc_u32 s51, s67, 0
	s_add_u32 s52, s66, 0x40b00
	s_addc_u32 s53, s67, 0
	s_add_u32 s54, s66, 0x40c00
	s_addc_u32 s55, s67, 0
	s_add_u32 s56, s66, 0x40d00
	s_addc_u32 s57, s67, 0
	s_add_u32 s58, s66, 0x40e00
	s_addc_u32 s59, s67, 0
	s_add_u32 s60, s66, 0x40f00
	s_addc_u32 s61, s67, 0
	s_add_u32 s62, s66, 0x41000
	s_mov_b64 s[28:29], s[64:65]
	s_addc_u32 s63, s67, 0
	s_mov_b64 s[30:31], s[66:67]
	s_add_u32 s64, s30, 0x41100
	s_addc_u32 s65, s31, 0
	s_add_u32 s66, s30, 0x41200
	s_addc_u32 s67, s31, 0
	s_add_u32 s68, s30, 0x41300
	s_addc_u32 s69, s31, 0
	s_mov_b32 s20, 1
	v_mov_b32_e32 v16, 0
	s_branch .LBB0_62
